# mix1a: same tile-order rotation (half of the blocks run retention kv-state tiles before pooling tiles)
# speedup vs baseline: 1.0053x; 1.0016x over previous
.LBB0_500:
	s_or_b64 exec, exec, s[0:1]
	s_cmpk_gt_i32 s2, 0x7ff
	s_waitcnt lgkmcnt(0)
	s_barrier
	s_cbranch_scc1 .LBB0_515
	v_xor_b32_e32 v1, v128, v131
	v_lshlrev_b32_e32 v1, 3, v1
	s_movk_i32 s1, 0x1e0
	v_and_b32_e32 v2, 56, v1
	v_and_b32_e32 v1, 0x60, v158
	v_and_or_b32 v4, v153, s1, v138
	v_bitop3_b32 v6, v128, v139, 3 bitop3:0x6c
	s_movk_i32 s0, 0x60
	v_lshlrev_b32_e32 v7, 4, v6
	v_lshlrev_b32_e32 v9, 7, v4
	v_lshlrev_b32_e32 v4, 7, v1
	v_and_b32_e32 v6, 0x1f0, v153
	s_movk_i32 s1, 0x50
	v_bitop3_b32 v24, v4, v6, s0 bitop3:0xf6
	s_movk_i32 s0, 0x70
	v_or_b32_e32 v13, v4, v6
	v_bitop3_b32 v15, v4, v6, 16 bitop3:0xf6
	v_bitop3_b32 v17, v4, v6, 32 bitop3:0xf6
	v_bitop3_b32 v19, v4, v6, 48 bitop3:0xf6
	v_bitop3_b32 v22, v4, v6, 64 bitop3:0xf6
	v_bitop3_b32 v23, v4, v6, s1 bitop3:0xf6
	v_bitop3_b32 v25, v4, v6, s0 bitop3:0xf6
	v_lshlrev_b32_e32 v10, 13, v135
	v_lshl_add_u32 v4, v134, 3, v138
	v_lshlrev_b32_e32 v8, 5, v138
	v_or3_b32 v67, v10, v137, v8
	v_add_u32_e32 v8, 0x60, v4
	v_lshl_or_b32 v6, v134, 11, v10
	v_and_b32_e32 v8, 0x7f, v8
	v_lshl_or_b32 v148, v4, 2, v6
	v_lshl_or_b32 v149, v8, 2, v6
	v_add_u32_e32 v4, 0x70, v4
	v_add_u32_e32 v8, 8, v133
	v_lshlrev_b32_e32 v12, 5, v135
	v_and_b32_e32 v4, 0x7f, v4
	v_and_b32_e32 v8, 0x78, v8
	v_mov_b32_e32 v65, 0
	v_lshl_or_b32 v150, v4, 2, v6
	v_or_b32_e32 v20, v134, v12
	v_lshlrev_b32_e32 v6, 9, v136
	v_lshlrev_b32_e32 v8, 2, v8
	v_or_b32_e32 v21, v136, v12
	v_add_u32_e32 v14, 16, v133
	v_lshlrev_b32_e32 v64, 1, v1
	v_lshlrev_b32_e32 v4, 7, v20
	v_or3_b32 v151, v10, v6, v8
	v_lshlrev_b32_e32 v6, 7, v21
	v_and_b32_e32 v14, 0x78, v14
	v_add_u32_e32 v16, 24, v133
	v_lshlrev_b32_e32 v68, 12, v20
	v_lshlrev_b32_e32 v70, 12, v21
	v_lshl_add_u64 v[20:21], s[50:51], 0, v[64:65]
	s_mov_b64 s[0:1], 0xba00000
	v_lshlrev_b32_e32 v64, 9, v157
	v_lshlrev_b32_e32 v8, 9, v132
	v_lshlrev_b32_e32 v14, 2, v14
	v_and_b32_e32 v16, 0x78, v16
	v_or_b32_e32 v18, 16, v12
	v_lshl_add_u64 v[84:85], v[20:21], 0, s[0:1]
	v_lshl_add_u64 v[20:21], s[50:51], 0, v[64:65]
	v_lshlrev_b32_e32 v64, 1, v2
	v_or3_b32 v160, v10, v8, v14
	v_or_b32_e32 v26, v132, v12
	v_lshlrev_b32_e32 v14, 9, v130
	v_lshlrev_b32_e32 v16, 2, v16
	v_or_b32_e32 v27, v130, v12
	v_or_b32_e32 v28, v18, v134
	v_or_b32_e32 v29, v136, v18
	v_or_b32_e32 v30, v132, v18
	v_or_b32_e32 v31, v130, v18
	v_lshl_add_u64 v[20:21], v[20:21], 0, v[64:65]
	s_mov_b64 s[0:1], 0x1000000
	v_and_b32_e32 v0, 0x7f000, v156
	v_and_b32_e32 v3, 14, v153
	v_lshlrev_b32_e32 v5, 7, v138
	v_lshlrev_b32_e32 v11, 4, v152
	v_lshlrev_b32_e32 v8, 7, v26
	v_or3_b32 v161, v10, v14, v16
	v_lshlrev_b32_e32 v10, 7, v27
	v_lshlrev_b32_e32 v12, 7, v28
	v_lshlrev_b32_e32 v14, 7, v29
	v_lshlrev_b32_e32 v16, 7, v30
	v_lshlrev_b32_e32 v18, 7, v31
	s_add_u32 s33, s50, 0x3a00000
	v_lshl_add_u64 v[86:87], v[20:21], 0, s[0:1]
	v_lshl_add_u64 v[20:21], s[50:51], 0, v[64:65]
	s_mov_b64 s[0:1], 0x1a00000
	v_lshlrev_b32_e32 v66, 3, v138
	v_and_b32_e32 v162, 0x70, v129
	v_mov_b32_e32 v69, v65
	v_mov_b32_e32 v71, v65
	v_lshlrev_b32_e32 v72, 12, v26
	v_mov_b32_e32 v73, v65
	v_lshlrev_b32_e32 v74, 12, v27
	v_mov_b32_e32 v75, v65
	v_lshlrev_b32_e32 v76, 12, v28
	v_mov_b32_e32 v77, v65
	v_lshlrev_b32_e32 v78, 12, v29
	v_mov_b32_e32 v79, v65
	v_lshlrev_b32_e32 v80, 12, v30
	v_mov_b32_e32 v81, v65
	v_lshlrev_b32_e32 v82, 12, v31
	v_mov_b32_e32 v83, v65
	s_addc_u32 s44, s51, 0
	v_lshl_add_u64 v[88:89], v[20:21], 0, s[0:1]
	s_mov_b32 s45, 0xc2fc0000
	s_mov_b32 s46, 0x3f2aaaab
	v_mov_b32_e32 v163, 0x3ecc95a3
	s_mov_b32 s47, 0x3f317218
	s_mov_b32 s52, 0x33800000
	s_mov_b32 s19, 0
	v_lshlrev_b32_e32 v90, 1, v0
	v_lshlrev_b32_e32 v92, 1, v2
	s_mov_b64 s[20:21], 0x40000
	v_add_u32_e32 v164, 0x1000, v129
	s_mov_b64 s[22:23], 0x80000
	v_add_u32_e32 v165, 0x2000, v129
	s_mov_b64 s[24:25], 0xc0000
	v_add_u32_e32 v166, 0x3000, v129
	s_movk_i32 s53, 0x7fff
	v_add_u32_e32 v167, v13, v3
	v_add_u32_e32 v168, v15, v3
	v_add_u32_e32 v169, v17, v3
	v_add_u32_e32 v170, v19, v3
	v_add_u32_e32 v171, v22, v3
	v_add_u32_e32 v172, v23, v3
	v_add_u32_e32 v173, v24, v3
	v_add_u32_e32 v174, v25, v3
	v_add_u32_e32 v175, v7, v9
	v_add_u32_e32 v176, v7, v5
	v_add_u32_e32 v177, v11, v9
	v_add_u32_e32 v178, v11, v5
	s_mov_b32 s54, 0x7060302
	v_lshlrev_b32_e32 v94, 1, v4
	v_lshlrev_b32_e32 v96, 1, v6
	v_lshlrev_b32_e32 v98, 1, v8
	v_lshlrev_b32_e32 v100, 1, v10
	v_lshlrev_b32_e32 v102, 1, v12
	v_lshlrev_b32_e32 v104, 1, v14
	v_lshlrev_b32_e32 v106, 1, v16
	v_lshlrev_b32_e32 v108, 1, v18
	s_mov_b64 s[26:27], 0x4000
	s_mov_b64 s[28:29], 0x8000
	s_mov_b64 s[30:31], 0xc000
	s_mov_b64 s[34:35], 0x10000
	s_movk_i32 s55, 0xf800
	v_mov_b32_e32 v179, 0x42800000
	v_mov_b32_e32 v180, 0x7fc00000
	v_mov_b32_e32 v181, 0xff800000
	s_mov_b32 s56, s2
	s_and_b32 s99, s2, 0x100
	s_lshl_b32 s99, s99, 2
	s_cmp_eq_u32 s3, 0x200
	s_cselect_b32 s99, s99, 0
	s_add_i32 s56, s56, s99
	s_branch .LBB0_503
.LBB0_502:
	s_add_i32 s56, s56, s3
	s_cmpk_lt_i32 s56, 0x800
	s_cbranch_scc1 .Lmy_m1a_chk
	s_cmp_eq_u32 s99, 0
	s_cbranch_scc1 .LBB0_515
	s_sub_i32 s56, s56, 0x800
.Lmy_m1a_chk:
	s_add_i32 s100, s2, s99
	s_cmp_eq_u32 s56, s100
	s_cbranch_scc1 .LBB0_515
